# L1 branch-GEMM phase: split-K mini unit of workgroups < 96 runs first (before the three full tiles) instead of last
# speedup vs baseline: 1.0087x; 1.0087x over previous
.LBB0_1546:
	s_and_b64 vcc, exec, s[2:3]
	s_cbranch_vccz .LBB0_1637
	v_mov_b32_e32 v12, v183
	v_mov_b32_e32 v174, 1
	v_ashrrev_i32_e32 v1, 31, v12
	v_lshrrev_b32_e32 v1, 26, v1
	v_add_u32_e32 v1, v12, v1
	v_ashrrev_i32_e32 v8, 6, v1
	v_bfe_i32 v1, v12, 27, 1
	v_lshlrev_b32_e32 v0, 4, v12
	v_lshrrev_b32_e32 v1, 22, v1
	v_add_u32_e32 v1, v0, v1
	v_and_b32_e32 v1, 0xfffffc00, v1
	v_sub_u32_e32 v1, v0, v1
	v_lshrrev_b32_e32 v2, 4, v1
	v_bitop3_b32 v1, v2, v1, 32 bitop3:0x6c
	v_ashrrev_i32_e32 v3, 31, v1
	v_lshrrev_b32_e32 v3, 26, v3
	v_add_u32_e32 v3, v1, v3
	v_lshlrev_b32_e32 v2, 3, v8
	v_ashrrev_i32_e32 v9, 6, v3
	v_and_b32_e32 v3, 0xc0, v3
	v_and_b32_e32 v2, -16, v2
	v_sub_u32_e32 v1, v1, v3
	v_add_u32_e32 v2, v9, v2
	v_ashrrev_i16_sdwa v1, v174, sext(v1) dst_sel:DWORD dst_unused:UNUSED_PAD src0_sel:DWORD src1_sel:BYTE_0
	v_lshlrev_b32_e32 v4, 5, v8
	v_bfe_i32 v10, v1, 0, 16
	v_lshlrev_b32_e32 v1, 1, v2
	v_lshrrev_b32_e32 v3, 2, v2
	v_and_b32_e32 v5, 3, v9
	s_mov_b32 s2, 0x1fffe0
	v_and_b32_e32 v4, 32, v4
	v_and_b32_e32 v1, 24, v1
	v_and_b32_e32 v3, 4, v3
	v_and_or_b32 v5, v2, s2, v5
	v_or3_b32 v1, v5, v3, v1
	v_add_lshl_u32 v3, v4, v10, 1
	v_add_u32_e32 v0, 0x2000, v0
	v_lshl_add_u32 v130, v1, 11, v3
	v_ashrrev_i32_e32 v1, 31, v0
	v_lshrrev_b32_e32 v1, 22, v1
	v_add_u32_e32 v1, v0, v1
	v_ashrrev_i32_e32 v11, 10, v1
	v_mul_i32_i24_e32 v1, 0x400, v11
	v_sub_u32_e32 v0, v0, v1
	v_lshrrev_b32_e32 v1, 4, v0
	v_bitop3_b32 v0, v1, v0, 32 bitop3:0x6c
	v_lshl_add_u32 v128, v2, 11, v3
	v_ashrrev_i32_e32 v2, 31, v0
	v_lshrrev_b32_e32 v2, 26, v2
	v_lshlrev_b32_e32 v1, 3, v11
	v_add_u32_e32 v2, v0, v2
	v_and_b32_e32 v1, -16, v1
	v_ashrrev_i32_e32 v13, 6, v2
	v_add_u32_e32 v1, v13, v1
	v_and_b32_e32 v4, 3, v13
	v_and_or_b32 v4, v1, s2, v4
	s_ashr_i32 s2, s20, 31
	s_lshr_b32 s2, s2, 29
	s_add_i32 s2, s20, s2
	s_ashr_i32 s2, s2, 3
	s_lshl_b32 s4, s20, 5
	s_mulk_i32 s2, 0xff01
	s_add_i32 s2, s2, s4
	s_ashr_i32 s4, s2, 31
	s_lshr_b32 s4, s4, 26
	s_add_i32 s4, s2, s4
	s_ashr_i32 s5, s4, 6
	s_andn2_b32 s4, s4, 63
	s_sub_i32 s4, s2, s4
	s_bfe_i32 s2, s4, 0x80000
	s_bfe_u32 s2, s2, 0x3000c
	s_add_i32 s8, s4, s2
	s_bfe_i32 s2, s8, 0x80000
	s_and_b32 s8, s8, 0xf8
	s_sub_i32 s4, s4, s8
	s_lshl_b32 s5, s5, 3
	s_sext_i32_i16 s2, s2
	s_sext_i32_i8 s4, s4
	v_readfirstlane_b32 s3, v12
	s_lshr_b32 s2, s2, 3
	s_add_i32 s12, s5, s4
	v_and_b32_e32 v2, 0xc0, v2
	s_ashr_i32 s16, s3, 6
	s_ashr_i32 s13, s12, 31
	s_bfe_i64 s[4:5], s[2:3], 0x100000
	s_ashr_i32 s26, s3, 8
	v_sub_u32_e32 v0, v0, v2
	s_lshl_b32 s50, s16, 10
	s_lshl_b64 s[8:9], s[12:13], 19
	s_lshl_b64 s[4:5], s[4:5], 19
	v_ashrrev_i16_sdwa v0, v174, sext(v0) dst_sel:DWORD dst_unused:UNUSED_PAD src0_sel:DWORD src1_sel:BYTE_0
	s_add_u32 s4, s25, s4
	v_lshlrev_b32_e32 v3, 5, v11
	v_bfe_i32 v14, v0, 0, 16
	v_lshlrev_b32_e32 v0, 1, v1
	v_lshrrev_b32_e32 v2, 2, v1
	s_addc_u32 s5, s33, s5
	s_cmpk_lt_i32 s20, 0x60
	s_cbranch_scc0 .Lmf_b_L1
	s_lshr_b32 s14, s20, 5
	s_lshl_b32 s14, s14, 22
	s_and_b32 s15, s20, 7
	s_lshl_b32 s15, s15, 19
	s_add_i32 s14, s14, s15
	s_bfe_u32 s15, s20, 0x20003
	s_lshl_b32 s15, s15, 9
	s_add_i32 s14, s14, s15
	s_add_u32 s4, s25, s14
	s_addc_u32 s5, s33, 0
.Lmf_b_L1:
	s_add_i32 s13, s50, 16
	v_and_b32_e32 v3, 32, v3
	v_and_b32_e32 v0, 24, v0
	v_and_b32_e32 v2, 4, v2
	s_add_i32 m0, s13, 0x10000
	v_or3_b32 v0, v4, v2, v0
	v_add_lshl_u32 v2, v3, v14, 1
	global_load_lds_dwordx4 v130, s[4:5]
	s_add_i32 m0, s13, 0x12000
	v_lshl_add_u32 v134, v0, 11, v2
	s_add_u32 s14, s4, 0x40000
	global_load_lds_dwordx4 v134, s[4:5]
	s_addc_u32 s15, s5, 0
	s_add_i32 m0, s13, 0x14000
	v_lshl_add_u32 v132, v1, 11, v2
	global_load_lds_dwordx4 v130, s[14:15]
	s_add_i32 m0, s13, 0x16000
	s_add_u32 s8, s21, s8
	s_addc_u32 s9, s24, s9
	s_cmpk_lt_i32 s20, 0x60
	s_cbranch_scc0 .Lmf_a_L1
	s_lshr_b32 vcc_lo, s20, 5
	s_mul_i32 vcc_lo, vcc_lo, 0x1080000
	s_add_i32 vcc_lo, vcc_lo, 0x1000000
	s_bfe_u32 vcc_hi, s20, 0x20003
	s_lshl_b32 vcc_hi, vcc_hi, 9
	s_add_i32 vcc_lo, vcc_lo, vcc_hi
	s_add_u32 s8, s21, vcc_lo
	s_addc_u32 s9, s24, 0
.Lmf_a_L1:
	s_add_i32 s51, s13, 0x2000
	global_load_lds_dwordx4 v134, s[14:15]
	s_mov_b32 m0, s13
	s_add_u32 s14, s8, 0x40000
	global_load_lds_dwordx4 v128, s[8:9]
	s_mov_b32 m0, s51
	s_addc_u32 s15, s9, 0
	s_add_i32 s52, s13, 0x4000
	global_load_lds_dwordx4 v132, s[8:9]
	s_mov_b32 m0, s52
	s_add_i32 s54, s13, 0x6000
	global_load_lds_dwordx4 v128, s[14:15]
	s_mov_b32 m0, s54
	v_mov_b32_e32 v131, 0
	global_load_lds_dwordx4 v132, s[14:15]
	v_mov_b32_e32 v135, v131
	v_mov_b32_e32 v129, v131
	v_mov_b32_e32 v133, v131
	s_cmp_eq_u32 s26, 1
	s_mov_b32 s74, 16
	v_lshl_add_u64 v[6:7], s[4:5], 0, v[130:131]
	v_lshl_add_u64 v[4:5], s[4:5], 0, v[134:135]
	v_lshl_add_u64 v[0:1], s[8:9], 0, v[128:129]
	s_cselect_b64 s[14:15], -1, 0
	s_cmp_lg_u32 s26, 1
	v_lshl_add_u64 v[2:3], s[8:9], 0, v[132:133]
	s_cbranch_scc1 .LBB0_1549
	s_barrier
.LBB0_1549:
	s_lshl_b32 s16, s16, 5
	s_and_b32 s30, s16, 0x60
	s_mov_b64 s[16:17], 0x80
	s_add_i32 m0, s13, 0x18000
	v_lshl_add_u64 v[6:7], v[6:7], 0, s[16:17]
	s_lshl_b32 s27, s26, 13
	s_lshl_b32 s31, s30, 7
	s_waitcnt vmcnt(2)
	s_barrier
	global_load_lds_dwordx4 v[6:7], off
	v_lshl_add_u64 v[4:5], v[4:5], 0, s[16:17]
	s_add_i32 m0, s13, 0x1a000
	s_add_i32 s55, s13, 0x8000
	s_add_i32 s56, s13, 0xa000
	global_load_lds_dwordx4 v[4:5], off
	v_lshl_add_u64 v[0:1], v[0:1], 0, s[16:17]
	s_mov_b32 m0, s55
	s_add_u32 s28, s4, 0x40080
	global_load_lds_dwordx4 v[0:1], off
	v_lshl_add_u64 v[0:1], v[2:3], 0, s[16:17]
	s_mov_b32 m0, s56
	s_addc_u32 s29, s5, 0
	global_load_lds_dwordx4 v[0:1], off
	s_add_i32 m0, s13, 0x1c000
	v_lshl_add_u64 v[0:1], s[28:29], 0, v[130:131]
	global_load_lds_dwordx4 v[0:1], off
	v_lshl_add_u64 v[0:1], s[28:29], 0, v[134:135]
	s_add_i32 m0, s13, 0x1e000
	s_movk_i32 s61, 0x1800
	global_load_lds_dwordx4 v[0:1], off
	v_lshrrev_b32_e32 v1, 1, v12
	v_and_b32_e32 v1, 24, v1
	v_and_b32_e32 v0, 15, v12
	v_lshlrev_b32_e32 v2, 1, v1
	v_lshl_or_b32 v136, s26, 6, v0
	v_lshl_or_b32 v0, v0, 6, v2
	v_lshlrev_b32_e32 v2, 2, v12
	v_and_b32_e32 v2, 32, v2
	v_bitop3_b32 v175, v0, s31, v2 bitop3:0xde
	v_bitop3_b32 v2, v0, s27, v2 bitop3:0xde
	v_or_b32_e32 v0, 16, v136
	v_or_b32_e32 v176, s30, v1
	v_ashrrev_i32_e32 v1, 31, v0
	v_lshlrev_b64 v[140:141], 13, v[0:1]
	v_or_b32_e32 v0, 32, v136
	v_ashrrev_i32_e32 v1, 31, v0
	v_lshlrev_b64 v[142:143], 13, v[0:1]
	v_or_b32_e32 v0, 48, v136
	v_ashrrev_i32_e32 v1, 31, v0
	v_add_u32_e32 v3, 0x2000, v136
	v_add_u32_e32 v4, 0x2010, v136
	v_add_u32_e32 v5, 0x2020, v136
	v_add_u32_e32 v6, 0x2030, v136
	v_lshlrev_b64 v[144:145], 13, v[0:1]
	v_mov_b64_e32 v[0:1], s[0:1]
	s_sext_i32_i8 s57, s2
	s_cmpk_lt_u32 s3, 0x100
	v_mad_i64_i32 v[146:147], s[2:3], v3, s61, v[0:1]
	v_mad_i64_i32 v[148:149], s[2:3], v4, s61, v[0:1]
	v_mad_i64_i32 v[150:151], s[2:3], v5, s61, v[0:1]
	v_mad_i64_i32 v[152:153], s[2:3], v6, s61, v[0:1]
	v_lshlrev_b32_e32 v0, 14, v11
	v_and_b32_e32 v0, 0xffff8000, v0
	v_lshl_add_u32 v0, v13, 11, v0
	v_and_b32_e32 v1, 1, v11
	v_lshl_or_b32 v0, v1, 6, v0
	v_lshl_add_u32 v154, v14, 1, v0
	v_lshlrev_b32_e32 v0, 14, v8
	v_and_b32_e32 v0, 0xffff8000, v0
	s_waitcnt vmcnt(6)
	s_cselect_b64 s[26:27], -1, 0
	s_cmpk_lt_i32 s20, 0x60
	v_lshl_add_u32 v0, v9, 11, v0
	v_and_b32_e32 v1, 1, v8
	v_ashrrev_i32_e32 v137, 31, v136
	s_cselect_b64 s[28:29], -1, 0
	s_bfe_u32 s59, s20, 0x20003
	s_mov_b32 s31, 0
	v_lshl_or_b32 v0, v1, 6, v0
	s_add_i32 s62, 16, 0x10000
	s_add_i32 s63, 16, 0x14000
	v_lshlrev_b64 v[138:139], 13, v[136:137]
	s_ashr_i32 s58, s20, 5
	s_lshl_b32 s30, s59, 9
	s_and_b32 s60, s20, 7
	v_mov_b32_e32 v155, v131
	v_lshl_add_u32 v156, v10, 1, v0
	v_mov_b32_e32 v157, v131
	s_mov_b32 s72, -1
	s_mov_b64 s[34:35], 0x100
	v_add_u32_e32 v137, s62, v175
	v_add_u32_e32 v177, s63, v175
	v_add_u32_e32 v178, 16, v2
	s_mov_b32 s36, 0x3b808081
	s_mov_b32 s75, s12
	s_mov_b32 s67, s57
	s_mov_b32 s73, s31
	s_mov_b32 s64, s31
	s_cmpk_lt_i32 s20, 0x60
	s_cselect_b32 s75, 32, s75
	s_cselect_b32 s67, s60, s67
	s_cselect_b32 s74, 4, s74
	s_cselect_b32 s72, s59, s72
	s_cselect_b32 s73, s58, s73
	s_barrier
	s_branch .LBB0_1552

.LBB0_1552:
	s_mov_b32 s2, s64
	s_add_i32 s64, s64, 1
	s_cmpk_lt_i32 s20, 0x60
	s_cselect_b32 vcc_lo, 3, 2
	s_cmp_lt_u32 s2, vcc_lo
	s_cselect_b64 s[2:3], -1, 0
	s_and_b64 vcc, exec, s[2:3]
	s_cbranch_vccnz .LBB0_1554
	s_mov_b32 s38, 32
	s_mov_b32 s65, 4
	s_mov_b64 s[46:47], s[30:31]
	s_mov_b32 s66, s59
	s_mov_b32 s40, s60
	s_mov_b32 s42, s58
	s_branch .LBB0_1555
.LBB0_1554:
	s_mov_b64 s[46:47], 0
	s_mov_b32 s65, 16
	s_mov_b32 s66, -1
	s_mov_b32 s40, s57
	s_mov_b32 s38, s12
	s_cmpk_lt_i32 s20, 0x60
	s_cselect_b32 s42, 1, 0
	s_sub_i32 s42, s64, s42
